# nt on all attention Q-row fragment loads (40 once-per-unit unshared loads) on top of phase_mod nt
# baseline (speedup 1.0000x reference)
.LBB0_606:
	s_ashr_i32 s7, s24, 10
	s_lshl_b32 s28, s7, 11
	s_lshl_b32 s14, s24, 5
	s_lshr_b32 s6, s24, 6
	s_addk_i32 s28, 0x2000
	s_and_b32 s31, s14, 0x7e0
	s_bfe_u32 s6, s6, 0x20002
	s_or_b32 s26, s28, s31
	s_lshl_b32 s29, s6, 6
	s_lshl_b32 s6, s6, 12
	s_bfe_u32 s27, s24, 0x40006
	s_lshl_b32 s30, s7, 8
	s_mul_i32 s15, s26, 0xc00
	s_mul_hi_i32 s14, s26, 0xc00
	s_add_u32 s15, s4, s15
	s_addc_u32 s18, s5, s14
	s_lshl_b32 s25, s27, 6
	s_lshl_b32 s14, s27, 7
	s_add_u32 s14, s15, s14
	s_addc_u32 s15, s18, 0
	v_mov_b32_e32 v107, v112
	v_mov_b32_e32 v109, v113
	v_mov_b64_e32 v[2:3], s[14:15]
	s_movk_i32 s14, 0xc00
	v_xor_b32_e32 v0, 32, v217
	v_mad_i64_i32 v[2:3], s[14:15], v107, s14, v[2:3]
	s_lshl_b32 s14, s7, 3
	s_ashr_i32 s15, s14, 31
	s_lshl_b64 s[18:19], s[14:15], 14
	s_add_u32 s7, s12, s18
	v_lshlrev_b32_e32 v4, 3, v109
	s_addc_u32 s15, s13, s19
	v_ashrrev_i32_e32 v5, 31, v4
	s_add_u32 s14, s7, s6
	v_lshl_add_u64 v[2:3], v[4:5], 1, v[2:3]
	s_addc_u32 s15, s15, 0
	global_load_dwordx4 v[50:53], v[2:3], off nt
	global_load_dwordx4 v[54:57], v[2:3], off offset:32 nt
	global_load_dwordx4 v[58:61], v[2:3], off offset:64 nt
	global_load_dwordx4 v[62:65], v[2:3], off offset:96 nt
	global_load_dwordx4 v[78:81], v104, s[14:15]
	global_load_dwordx4 v[74:77], v104, s[14:15] offset:1024
	global_load_dwordx4 v[70:73], v104, s[14:15] offset:2048
	global_load_dwordx4 v[66:69], v104, s[14:15] offset:3072
	s_load_dwordx4 s[36:39], s[48:49], 0x140
	v_and_b32_e32 v2, 64, v217
	s_or_b32 s14, s30, s29
	v_add_u32_e32 v2, 64, v2
	s_mul_i32 s30, s14, 0x1200
	v_cmp_lt_i32_e32 vcc, v0, v2
	s_mul_hi_i32 s29, s14, 0x1200
	s_waitcnt lgkmcnt(0)
	s_add_u32 s14, s38, s30
	v_cndmask_b32_e32 v0, v217, v0, vcc
	s_addc_u32 s15, s39, s29
	s_or_b32 s18, s18, s6
	v_mov_b32_e32 v2, v1
	v_mov_b32_e32 v3, v1
	v_mov_b32_e32 v4, v1
	v_mov_b32_e32 v5, v1
	v_mov_b32_e32 v6, v1
	v_mov_b32_e32 v7, v1
	v_mov_b32_e32 v8, v1
	v_mov_b32_e32 v9, v1
	v_mov_b32_e32 v10, v1
	v_mov_b32_e32 v11, v1
	v_mov_b32_e32 v12, v1
	v_mov_b32_e32 v13, v1
	v_mov_b32_e32 v14, v1
	v_mov_b32_e32 v15, v1
	v_mov_b32_e32 v16, v1
	v_mov_b32_e32 v17, v1
	v_mov_b32_e32 v18, v1
	v_mov_b32_e32 v19, v1
	v_mov_b32_e32 v20, v1
	v_mov_b32_e32 v21, v1
	v_mov_b32_e32 v22, v1
	v_mov_b32_e32 v23, v1
	v_mov_b32_e32 v24, v1
	v_mov_b32_e32 v25, v1
	v_mov_b32_e32 v26, v1
	v_mov_b32_e32 v27, v1
	v_mov_b32_e32 v28, v1
	v_mov_b32_e32 v29, v1
	v_mov_b32_e32 v30, v1
	v_mov_b32_e32 v31, v1
	v_lshlrev_b32_e32 v114, 2, v0
	s_add_u32 s18, s16, s18
	v_mov_b32_e32 v0, v1
	v_mov_b64_e32 v[32:33], v[30:31]
	s_mov_b32 s7, s56
	s_mov_b32 s34, 7
	s_addc_u32 s19, s17, s19
	v_mov_b32_e32 v108, 0
	v_mov_b32_e32 v115, 0xf149f2ca
	v_mov_b64_e32 v[30:31], v[28:29]
	v_mov_b64_e32 v[28:29], v[26:27]
	v_mov_b64_e32 v[26:27], v[24:25]
	v_mov_b64_e32 v[24:25], v[22:23]
	v_mov_b64_e32 v[22:23], v[20:21]
	v_mov_b64_e32 v[20:21], v[18:19]
	v_mov_b64_e32 v[18:19], v[16:17]
	v_mov_b64_e32 v[16:17], v[14:15]
	v_mov_b64_e32 v[14:15], v[12:13]
	v_mov_b64_e32 v[12:13], v[10:11]
	v_mov_b64_e32 v[10:11], v[8:9]
	v_mov_b64_e32 v[8:9], v[6:7]
	v_mov_b64_e32 v[6:7], v[4:5]
	v_mov_b64_e32 v[4:5], v[2:3]
	v_mov_b64_e32 v[2:3], v[0:1]
	s_branch .LBB0_608

.LBB0_625:
	s_lshr_b32 s7, s13, 3
	s_bfe_u32 s24, s7, 0x20002
	s_load_dwordx4 s[28:31], s[48:49], 0x140
	s_and_b32 s6, s10, 0xffffff00
	s_lshl_b32 s19, s24, 6
	s_or_b32 s6, s6, s19
	s_ashr_i32 s7, s6, 31
	s_lshl_b64 s[6:7], s[6:7], 9
	s_waitcnt lgkmcnt(0)
	s_add_u32 s6, s30, s6
	s_addc_u32 s7, s31, s7
	s_lshl_b32 s14, s13, 1
	s_and_b32 s23, s14, 0xffffff00
	s_lshl_b32 s14, s13, 5
	s_and_b32 s14, s14, 0xe0
	s_or_b32 s17, s23, s14
	s_bfe_u32 s18, s13, 0x40003
	s_mul_i32 s15, s17, 0xc00
	s_mul_hi_i32 s14, s17, 0xc00
	s_add_u32 s15, s4, s15
	s_addc_u32 s25, s5, s14
	s_lshl_b32 s16, s18, 6
	s_lshl_b32 s14, s18, 7
	s_add_u32 s14, s15, s14
	s_addc_u32 s15, s25, 0
	v_mov_b32_e32 v105, v103
	s_waitcnt vmcnt(1)
	v_mov_b32_e32 v106, v102
	v_mov_b64_e32 v[2:3], s[14:15]
	s_movk_i32 s14, 0xc00
	v_xor_b32_e32 v0, 32, v217
	v_mad_i64_i32 v[2:3], s[14:15], v106, s14, v[2:3]
	s_ashr_i32 s14, s23, 5
	s_ashr_i32 s15, s14, 31
	s_lshl_b64 s[14:15], s[14:15], 14
	s_add_u32 s25, s8, s14
	v_lshlrev_b32_e32 v4, 3, v105
	s_addc_u32 s26, s9, s15
	s_lshl_b32 s27, s24, 12
	v_ashrrev_i32_e32 v5, 31, v4
	s_add_u32 s24, s25, s27
	v_lshl_add_u64 v[2:3], v[4:5], 1, v[2:3]
	s_addc_u32 s25, s26, 0
	global_load_dwordx4 v[62:65], v[2:3], off nt
	global_load_dwordx4 v[58:61], v[2:3], off offset:32 nt
	global_load_dwordx4 v[54:57], v[2:3], off offset:64 nt
	global_load_dwordx4 v[50:53], v[2:3], off offset:96 nt
	global_load_dwordx4 v[78:81], v104, s[24:25]
	global_load_dwordx4 v[74:77], v104, s[24:25] offset:1024
	global_load_dwordx4 v[70:73], v104, s[24:25] offset:2048
	global_load_dwordx4 v[66:69], v104, s[24:25] offset:3072
	v_and_b32_e32 v2, 64, v217
	v_add_u32_e32 v2, 64, v2
	v_cmp_lt_i32_e32 vcc, v0, v2
	s_or_b32 s14, s14, s27
	v_mov_b32_e32 v2, v1
	v_cndmask_b32_e32 v0, v217, v0, vcc
	v_mov_b32_e32 v3, v1
	v_mov_b32_e32 v4, v1
	v_mov_b32_e32 v5, v1
	v_mov_b32_e32 v6, v1
	v_mov_b32_e32 v7, v1
	v_mov_b32_e32 v8, v1
	v_mov_b32_e32 v9, v1
	v_mov_b32_e32 v10, v1
	v_mov_b32_e32 v11, v1
	v_mov_b32_e32 v12, v1
	v_mov_b32_e32 v13, v1
	s_waitcnt vmcnt(8)
	v_mov_b32_e32 v14, v1
	v_mov_b32_e32 v15, v1
	v_mov_b32_e32 v16, v1
	v_mov_b32_e32 v17, v1
	v_mov_b32_e32 v18, v1
	v_mov_b32_e32 v19, v1
	v_mov_b32_e32 v20, v1
	v_mov_b32_e32 v21, v1
	v_mov_b32_e32 v22, v1
	v_mov_b32_e32 v23, v1
	v_mov_b32_e32 v24, v1
	v_mov_b32_e32 v25, v1
	v_mov_b32_e32 v26, v1
	v_mov_b32_e32 v27, v1
	v_mov_b32_e32 v28, v1
	v_mov_b32_e32 v29, v1
	v_mov_b32_e32 v30, v1
	v_mov_b32_e32 v31, v1
	v_lshlrev_b32_e32 v108, 2, v0
	s_add_u32 s14, s11, s14
	v_mov_b32_e32 v0, v1
	v_mov_b64_e32 v[32:33], v[30:31]
	s_mov_b32 s24, 7
	s_addc_u32 s15, s12, s15
	v_mov_b32_e32 v109, 0
	v_mov_b32_e32 v107, 0xf149f2ca
	v_mov_b64_e32 v[30:31], v[28:29]
	v_mov_b64_e32 v[28:29], v[26:27]
	v_mov_b64_e32 v[26:27], v[24:25]
	v_mov_b64_e32 v[24:25], v[22:23]
	v_mov_b64_e32 v[22:23], v[20:21]
	v_mov_b64_e32 v[20:21], v[18:19]
	v_mov_b64_e32 v[18:19], v[16:17]
	v_mov_b64_e32 v[16:17], v[14:15]
	v_mov_b64_e32 v[14:15], v[12:13]
	v_mov_b64_e32 v[12:13], v[10:11]
	v_mov_b64_e32 v[10:11], v[8:9]
	v_mov_b64_e32 v[8:9], v[6:7]
	v_mov_b64_e32 v[6:7], v[4:5]
	v_mov_b64_e32 v[4:5], v[2:3]
	v_mov_b64_e32 v[2:3], v[0:1]
	s_branch .LBB0_627

.LBB0_632:
	s_and_b64 vcc, exec, s[0:1]
	s_cbranch_vccz .LBB0_657
	s_waitcnt lgkmcnt(0)
	s_load_dwordx4 s[24:27], s[48:49], 0x140
	v_readlane_b32 s0, v252, 14
	s_add_i32 s1, s53, s0
	s_ashr_i32 s0, s1, 6
	v_readlane_b32 s4, v252, 15
	s_add_i32 s18, s0, s4
	s_waitcnt lgkmcnt(0)
	s_add_u32 s5, s26, 0x6500000
	s_addc_u32 s8, s27, 0
	s_lshl_b32 s1, s1, 5
	s_and_b32 s9, s1, 0x7e0
	v_readlane_b32 s1, v252, 16
	s_or_b32 s4, s9, s1
	s_ashr_i32 s0, s18, 2
	s_mul_i32 s1, s4, 0xc00
	s_add_u32 s1, s5, s1
	s_addc_u32 s10, s8, 0
	s_lshl_b32 s14, s18, 6
	s_ashr_i32 s15, s14, 31
	s_lshl_b64 s[6:7], s[14:15], 1
	s_add_u32 s6, s1, s6
	s_waitcnt vmcnt(0)
	v_and_b32_e32 v110, 31, v240
	v_lshrrev_b32_e32 v111, 5, v194
	s_addc_u32 s7, s10, s7
	v_mov_b32_e32 v101, v110
	v_mov_b32_e32 v103, v111
	v_mov_b64_e32 v[2:3], s[6:7]
	s_movk_i32 s1, 0xc00
	v_lshlrev_b32_e32 v98, 4, v194
	v_mad_i64_i32 v[2:3], s[6:7], v101, s1, v[2:3]
	s_lshl_b32 s1, s0, 6
	v_readlane_b32 s6, v252, 17
	s_add_i32 s11, s1, s6
	s_ashr_i32 s1, s0, 31
	v_readlane_b32 s6, v254, 2
	s_add_u32 s6, s26, s6
	v_lshlrev_b32_e32 v4, 3, v103
	s_addc_u32 s7, s27, 0
	s_lshl_b64 s[0:1], s[0:1], 12
	v_ashrrev_i32_e32 v5, 31, v4
	s_add_u32 s6, s6, s0
	v_lshl_add_u64 v[2:3], v[4:5], 1, v[2:3]
	s_addc_u32 s7, s7, s1
	v_mov_b32_e32 v99, v1
	global_load_dwordx4 v[50:53], v[2:3], off nt
	global_load_dwordx4 v[54:57], v[2:3], off offset:32 nt
	global_load_dwordx4 v[58:61], v[2:3], off offset:64 nt
	global_load_dwordx4 v[62:65], v[2:3], off offset:96 nt
	v_lshl_add_u64 v[2:3], s[6:7], 0, v[98:99]
	s_mov_b64 s[6:7], 0xf500000
	v_lshl_add_u64 v[4:5], v[2:3], 0, s[6:7]
	s_mov_b32 s6, 0xf500000
	v_add_co_u32_e32 v2, vcc, s6, v2
	s_mul_hi_i32 s10, s11, 0x1200
	s_nop 0
	v_addc_co_u32_e32 v3, vcc, 0, v3, vcc
	global_load_dwordx4 v[74:77], v[4:5], off offset:1024
	global_load_dwordx4 v[70:73], v[4:5], off offset:2048
	global_load_dwordx4 v[78:81], v[2:3], off
	global_load_dwordx4 v[66:69], v[4:5], off offset:3072
	s_mulk_i32 s11, 0x1200
	v_and_b32_e32 v2, 64, v217
	s_add_u32 s6, s26, s11
	v_xor_b32_e32 v0, 32, v217
	v_add_u32_e32 v2, 64, v2
	s_addc_u32 s7, s27, s10
	v_readlane_b32 s12, v254, 3
	v_cmp_lt_i32_e32 vcc, v0, v2
	s_add_u32 s12, s26, s12
	s_addc_u32 s13, s27, 0
	v_cndmask_b32_e32 v0, v217, v0, vcc
	v_mov_b32_e32 v2, v1
	v_mov_b32_e32 v3, v1
	v_mov_b32_e32 v4, v1
	v_mov_b32_e32 v5, v1
	v_mov_b32_e32 v6, v1
	v_mov_b32_e32 v7, v1
	v_mov_b32_e32 v8, v1
	v_mov_b32_e32 v9, v1
	v_mov_b32_e32 v10, v1
	v_mov_b32_e32 v11, v1
	v_mov_b32_e32 v12, v1
	v_mov_b32_e32 v13, v1
	v_mov_b32_e32 v14, v1
	v_mov_b32_e32 v15, v1
	v_mov_b32_e32 v16, v1
	v_mov_b32_e32 v17, v1
	v_mov_b32_e32 v18, v1
	v_mov_b32_e32 v19, v1
	v_mov_b32_e32 v20, v1
	v_mov_b32_e32 v21, v1
	v_mov_b32_e32 v22, v1
	v_mov_b32_e32 v23, v1
	v_mov_b32_e32 v24, v1
	v_mov_b32_e32 v25, v1
	v_mov_b32_e32 v26, v1
	v_mov_b32_e32 v27, v1
	v_mov_b32_e32 v28, v1
	v_mov_b32_e32 v29, v1
	v_mov_b32_e32 v30, v1
	v_mov_b32_e32 v31, v1
	v_lshlrev_b32_e32 v112, 2, v0
	s_add_u32 s24, s12, s0
	v_mov_b32_e32 v0, v1
	v_mov_b64_e32 v[32:33], v[30:31]
	v_lshlrev_b32_e32 v100, 3, v194
	s_addc_u32 s25, s13, s1
	v_mov_b32_e32 v102, 0
	v_mov_b32_e32 v106, 0xf149f2ca
	s_mov_b32 s12, 7
	v_mov_b64_e32 v[30:31], v[28:29]
	v_mov_b64_e32 v[28:29], v[26:27]
	v_mov_b64_e32 v[26:27], v[24:25]
	v_mov_b64_e32 v[24:25], v[22:23]
	v_mov_b64_e32 v[22:23], v[20:21]
	v_mov_b64_e32 v[20:21], v[18:19]
	v_mov_b64_e32 v[18:19], v[16:17]
	v_mov_b64_e32 v[16:17], v[14:15]
	v_mov_b64_e32 v[14:15], v[12:13]
	v_mov_b64_e32 v[12:13], v[10:11]
	v_mov_b64_e32 v[10:11], v[8:9]
	v_mov_b64_e32 v[8:9], v[6:7]
	v_mov_b64_e32 v[6:7], v[4:5]
	v_mov_b64_e32 v[4:5], v[2:3]
	v_mov_b64_e32 v[2:3], v[0:1]
	s_branch .LBB0_635

.LBB0_651:
	v_readlane_b32 s9, v252, 18
	s_or_b32 s26, s10, s9
	s_xor_b64 s[24:25], s[16:17], -1
	s_lshl_b32 s9, s26, 6
	s_lshl_b32 s10, s26, 7
	s_add_u32 s10, s5, s10
	v_mov_b32_e32 v113, v111
	v_mov_b32_e32 v114, v110
	s_addc_u32 s11, s8, 0
	v_mov_b64_e32 v[2:3], s[10:11]
	s_movk_i32 s10, 0xc00
	v_lshlrev_b32_e32 v4, 3, v113
	v_mad_i64_i32 v[2:3], s[10:11], v114, s10, v[2:3]
	v_ashrrev_i32_e32 v5, 31, v4
	v_lshl_add_u64 v[2:3], v[4:5], 1, v[2:3]
	global_load_dwordx4 v[62:65], v[2:3], off nt
	global_load_dwordx4 v[58:61], v[2:3], off offset:32 nt
	global_load_dwordx4 v[54:57], v[2:3], off offset:64 nt
	global_load_dwordx4 v[50:53], v[2:3], off offset:96 nt
	global_load_dwordx4 v[74:77], v[100:101], off
	global_load_dwordx4 v[70:73], v[100:101], off offset:1024
	global_load_dwordx4 v[66:69], v[100:101], off offset:2048
	global_load_dwordx4 v[78:81], v[100:101], off offset:3072
	v_mov_b32_e32 v2, v1
	v_mov_b32_e32 v3, v1
	v_mov_b32_e32 v4, v1
	v_mov_b32_e32 v5, v1
	v_mov_b32_e32 v6, v1
	v_mov_b32_e32 v7, v1
	v_mov_b32_e32 v8, v1
	v_mov_b32_e32 v9, v1
	v_mov_b32_e32 v10, v1
	v_mov_b32_e32 v11, v1
	v_mov_b32_e32 v12, v1
	v_mov_b32_e32 v13, v1
	v_mov_b32_e32 v14, v1
	v_mov_b32_e32 v15, v1
	v_mov_b32_e32 v16, v1
	v_mov_b32_e32 v17, v1
	v_mov_b32_e32 v18, v1
	v_mov_b32_e32 v19, v1
	v_mov_b32_e32 v20, v1
	v_mov_b32_e32 v21, v1
	v_mov_b32_e32 v22, v1
	v_mov_b32_e32 v23, v1
	v_mov_b32_e32 v24, v1
	v_mov_b32_e32 v25, v1
	v_mov_b32_e32 v26, v1
	v_mov_b32_e32 v27, v1
	v_mov_b32_e32 v28, v1
	v_mov_b32_e32 v29, v1
	v_mov_b32_e32 v30, v1
	v_mov_b32_e32 v31, v1
	v_mov_b32_e32 v0, v1
	v_mov_b64_e32 v[32:33], v[30:31]
	s_mov_b32 s10, 7
	v_mov_b32_e32 v116, 0
	v_mov_b32_e32 v115, 0xf149f2ca
	s_mov_b64 s[28:29], s[18:19]
	s_mov_b64 s[30:31], s[14:15]
	v_mov_b64_e32 v[30:31], v[28:29]
	v_mov_b64_e32 v[28:29], v[26:27]
	v_mov_b64_e32 v[26:27], v[24:25]
	v_mov_b64_e32 v[24:25], v[22:23]
	v_mov_b64_e32 v[22:23], v[20:21]
	v_mov_b64_e32 v[20:21], v[18:19]
	v_mov_b64_e32 v[18:19], v[16:17]
	v_mov_b64_e32 v[16:17], v[14:15]
	v_mov_b64_e32 v[14:15], v[12:13]
	v_mov_b64_e32 v[12:13], v[10:11]
	v_mov_b64_e32 v[10:11], v[8:9]
	v_mov_b64_e32 v[8:9], v[6:7]
	v_mov_b64_e32 v[6:7], v[4:5]
	v_mov_b64_e32 v[4:5], v[2:3]
	v_mov_b64_e32 v[2:3], v[0:1]
	s_branch .LBB0_653

.LBB0_666:
	s_xor_b64 s[14:15], s[14:15], -1
	s_lshl_b32 s19, s18, 7
	s_add_u32 s24, s16, s19
	v_mov_b32_e32 v0, v188
	v_mov_b32_e32 v4, v189
	s_addc_u32 s25, s17, 0
	v_mov_b64_e32 v[2:3], s[24:25]
	v_mad_i64_i32 v[2:3], s[24:25], v0, s76, v[2:3]
	v_lshlrev_b32_e32 v4, 3, v4
	v_ashrrev_i32_e32 v5, 31, v4
	s_lshl_b32 s24, s18, 12
	v_lshl_add_u64 v[2:3], v[4:5], 1, v[2:3]
	s_or_b32 s18, s24, s13
	s_mov_b32 s19, s56
	global_load_dwordx4 v[108:111], v[2:3], off nt
	global_load_dwordx4 v[104:107], v[2:3], off offset:32 nt
	global_load_dwordx4 v[100:103], v[2:3], off offset:64 nt
	global_load_dwordx4 v[96:99], v[2:3], off offset:96 nt
	v_lshl_add_u64 v[2:3], v[170:171], 0, s[18:19]
	global_load_dwordx4 v[124:127], v[2:3], off
	global_load_dwordx4 v[120:123], v[2:3], off offset:1024
	global_load_dwordx4 v[116:119], v[2:3], off offset:2048
	global_load_dwordx4 v[112:115], v[2:3], off offset:3072
	s_add_i32 s18, s13, s24
	v_mov_b32_e32 v14, v1
	v_mov_b32_e32 v15, v1
	s_add_u32 s18, s23, s18
	v_mov_b32_e32 v0, v1
	v_mov_b32_e32 v2, v1
	v_mov_b32_e32 v3, v1
	v_mov_b32_e32 v4, v1
	v_mov_b32_e32 v5, v1
	v_mov_b32_e32 v6, v1
	v_mov_b32_e32 v7, v1
	v_mov_b32_e32 v8, v1
	v_mov_b32_e32 v9, v1
	v_mov_b32_e32 v10, v1
	v_mov_b32_e32 v11, v1
	v_mov_b32_e32 v12, v1
	v_mov_b32_e32 v13, v1
	v_mov_b64_e32 v[30:31], v[14:15]
	v_mov_b64_e32 v[46:47], v[14:15]
	v_mov_b64_e32 v[62:63], v[14:15]
	v_mov_b64_e32 v[78:79], v[14:15]
	s_mov_b32 s27, 7
	s_addc_u32 s19, s26, 0
	v_mov_b32_e32 v191, 0
	v_mov_b32_e32 v192, 0xf149f2ca
	s_mov_b64 s[24:25], s[6:7]
	v_mov_b64_e32 v[28:29], v[12:13]
	v_mov_b64_e32 v[26:27], v[10:11]
	v_mov_b64_e32 v[24:25], v[8:9]
	v_mov_b64_e32 v[22:23], v[6:7]
	v_mov_b64_e32 v[20:21], v[4:5]
	v_mov_b64_e32 v[18:19], v[2:3]
	v_mov_b64_e32 v[16:17], v[0:1]
	v_mov_b64_e32 v[44:45], v[12:13]
	v_mov_b64_e32 v[42:43], v[10:11]
	v_mov_b64_e32 v[40:41], v[8:9]
	v_mov_b64_e32 v[38:39], v[6:7]
	v_mov_b64_e32 v[36:37], v[4:5]
	v_mov_b64_e32 v[34:35], v[2:3]
	v_mov_b64_e32 v[32:33], v[0:1]
	v_mov_b64_e32 v[60:61], v[12:13]
	v_mov_b64_e32 v[58:59], v[10:11]
	v_mov_b64_e32 v[56:57], v[8:9]
	v_mov_b64_e32 v[54:55], v[6:7]
	v_mov_b64_e32 v[52:53], v[4:5]
	v_mov_b64_e32 v[50:51], v[2:3]
	v_mov_b64_e32 v[48:49], v[0:1]
	v_mov_b64_e32 v[76:77], v[12:13]
	v_mov_b64_e32 v[74:75], v[10:11]
	v_mov_b64_e32 v[72:73], v[8:9]
	v_mov_b64_e32 v[70:71], v[6:7]
	v_mov_b64_e32 v[68:69], v[4:5]
	v_mov_b64_e32 v[66:67], v[2:3]
	v_mov_b64_e32 v[64:65], v[0:1]
	s_branch .LBB0_668

.LBB0_683:
	s_xor_b64 s[14:15], s[14:15], -1
	s_lshl_b32 s19, s18, 7
	s_add_u32 s24, s29, s19
	v_mov_b32_e32 v0, v212
	v_mov_b32_e32 v4, v214
	s_addc_u32 s25, s30, 0
	v_mov_b64_e32 v[2:3], s[24:25]
	v_mad_i64_i32 v[2:3], s[24:25], v0, s76, v[2:3]
	v_lshlrev_b32_e32 v4, 3, v4
	v_ashrrev_i32_e32 v5, 31, v4
	s_lshl_b32 s24, s18, 12
	v_lshl_add_u64 v[2:3], v[4:5], 1, v[2:3]
	s_or_b32 s18, s24, s28
	s_mov_b32 s19, s56
	global_load_dwordx4 v[108:111], v[2:3], off nt
	global_load_dwordx4 v[104:107], v[2:3], off offset:32 nt
	global_load_dwordx4 v[100:103], v[2:3], off offset:64 nt
	global_load_dwordx4 v[96:99], v[2:3], off offset:96 nt
	v_lshl_add_u64 v[2:3], v[172:173], 0, s[18:19]
	global_load_dwordx4 v[124:127], v[2:3], off
	global_load_dwordx4 v[120:123], v[2:3], off offset:1024
	global_load_dwordx4 v[116:119], v[2:3], off offset:2048
	global_load_dwordx4 v[112:115], v[2:3], off offset:3072
	s_add_i32 s37, s28, s24
	v_mov_b32_e32 v14, v1
	v_mov_b32_e32 v15, v1
	s_add_u32 s24, s31, s37
	v_mov_b32_e32 v0, v1
	v_mov_b32_e32 v2, v1
	v_mov_b32_e32 v3, v1
	v_mov_b32_e32 v4, v1
	v_mov_b32_e32 v5, v1
	v_mov_b32_e32 v6, v1
	v_mov_b32_e32 v7, v1
	v_mov_b32_e32 v8, v1
	v_mov_b32_e32 v9, v1
	v_mov_b32_e32 v10, v1
	v_mov_b32_e32 v11, v1
	v_mov_b32_e32 v12, v1
	v_mov_b32_e32 v13, v1
	v_mov_b64_e32 v[30:31], v[14:15]
	v_mov_b64_e32 v[46:47], v[14:15]
	v_mov_b64_e32 v[62:63], v[14:15]
	v_mov_b64_e32 v[78:79], v[14:15]
	s_mov_b32 s38, 7
	s_addc_u32 s25, s34, 0
	v_mov_b32_e32 v218, 0
	v_mov_b32_e32 v171, 0xf149f2ca
	s_mov_b64 s[26:27], s[6:7]
	v_mov_b64_e32 v[28:29], v[12:13]
	v_mov_b64_e32 v[26:27], v[10:11]
	v_mov_b64_e32 v[24:25], v[8:9]
	v_mov_b64_e32 v[22:23], v[6:7]
	v_mov_b64_e32 v[20:21], v[4:5]
	v_mov_b64_e32 v[18:19], v[2:3]
	v_mov_b64_e32 v[16:17], v[0:1]
	v_mov_b64_e32 v[44:45], v[12:13]
	v_mov_b64_e32 v[42:43], v[10:11]
	v_mov_b64_e32 v[40:41], v[8:9]
	v_mov_b64_e32 v[38:39], v[6:7]
	v_mov_b64_e32 v[36:37], v[4:5]
	v_mov_b64_e32 v[34:35], v[2:3]
	v_mov_b64_e32 v[32:33], v[0:1]
	v_mov_b64_e32 v[60:61], v[12:13]
	v_mov_b64_e32 v[58:59], v[10:11]
	v_mov_b64_e32 v[56:57], v[8:9]
	v_mov_b64_e32 v[54:55], v[6:7]
	v_mov_b64_e32 v[52:53], v[4:5]
	v_mov_b64_e32 v[50:51], v[2:3]
	v_mov_b64_e32 v[48:49], v[0:1]
	v_mov_b64_e32 v[76:77], v[12:13]
	v_mov_b64_e32 v[74:75], v[10:11]
	v_mov_b64_e32 v[72:73], v[8:9]
	v_mov_b64_e32 v[70:71], v[6:7]
	v_mov_b64_e32 v[68:69], v[4:5]
	v_mov_b64_e32 v[66:67], v[2:3]
	v_mov_b64_e32 v[64:65], v[0:1]
	s_branch .LBB0_685

.LBB0_705:
	s_lshl_b32 s13, s9, 7
	s_add_u32 s16, s11, s13
	v_mov_b32_e32 v0, v205
	v_mov_b32_e32 v4, v206
	s_addc_u32 s17, s12, 0
	v_mov_b64_e32 v[2:3], s[16:17]
	v_mad_i64_i32 v[2:3], s[16:17], v0, s76, v[2:3]
	v_lshlrev_b32_e32 v4, 3, v4
	v_readlane_b32 s13, v252, 27
	v_ashrrev_i32_e32 v5, 31, v4
	s_add_i32 s16, s9, s13
	s_mov_b32 s17, s56
	v_lshl_add_u64 v[2:3], v[4:5], 1, v[2:3]
	s_lshl_b64 s[24:25], s[16:17], 12
	global_load_dwordx4 v[108:111], v[2:3], off nt
	global_load_dwordx4 v[104:107], v[2:3], off offset:32 nt
	global_load_dwordx4 v[100:103], v[2:3], off offset:64 nt
	global_load_dwordx4 v[96:99], v[2:3], off offset:96 nt
	v_lshl_add_u64 v[2:3], v[152:153], 0, s[24:25]
	global_load_dwordx4 v[124:127], v[2:3], off
	global_load_dwordx4 v[120:123], v[2:3], off offset:1024
	global_load_dwordx4 v[116:119], v[2:3], off offset:2048
	global_load_dwordx4 v[112:115], v[2:3], off offset:3072
	v_mov_b32_e32 v14, v1
	v_mov_b32_e32 v15, v1
	v_mov_b32_e32 v0, v1
	v_mov_b32_e32 v2, v1
	v_mov_b32_e32 v3, v1
	v_mov_b32_e32 v4, v1
	v_mov_b32_e32 v5, v1
	v_mov_b32_e32 v6, v1
	v_mov_b32_e32 v7, v1
	v_mov_b32_e32 v8, v1
	v_mov_b32_e32 v9, v1
	v_mov_b32_e32 v10, v1
	v_mov_b32_e32 v11, v1
	v_mov_b32_e32 v12, v1
	v_mov_b32_e32 v13, v1
	v_mov_b64_e32 v[30:31], v[14:15]
	v_mov_b64_e32 v[46:47], v[14:15]
	v_mov_b64_e32 v[62:63], v[14:15]
	v_mov_b64_e32 v[78:79], v[14:15]
	s_mov_b32 s13, 7
	v_mov_b32_e32 v209, 0
	v_mov_b32_e32 v208, 0xf149f2ca
	s_mov_b64 s[26:27], s[14:15]
	s_mov_b64 s[28:29], s[6:7]
	v_mov_b64_e32 v[28:29], v[12:13]
	v_mov_b64_e32 v[26:27], v[10:11]
	v_mov_b64_e32 v[24:25], v[8:9]
	v_mov_b64_e32 v[22:23], v[6:7]
	v_mov_b64_e32 v[20:21], v[4:5]
	v_mov_b64_e32 v[18:19], v[2:3]
	v_mov_b64_e32 v[16:17], v[0:1]
	v_mov_b64_e32 v[44:45], v[12:13]
	v_mov_b64_e32 v[42:43], v[10:11]
	v_mov_b64_e32 v[40:41], v[8:9]
	v_mov_b64_e32 v[38:39], v[6:7]
	v_mov_b64_e32 v[36:37], v[4:5]
	v_mov_b64_e32 v[34:35], v[2:3]
	v_mov_b64_e32 v[32:33], v[0:1]
	v_mov_b64_e32 v[60:61], v[12:13]
	v_mov_b64_e32 v[58:59], v[10:11]
	v_mov_b64_e32 v[56:57], v[8:9]
	v_mov_b64_e32 v[54:55], v[6:7]
	v_mov_b64_e32 v[52:53], v[4:5]
	v_mov_b64_e32 v[50:51], v[2:3]
	v_mov_b64_e32 v[48:49], v[0:1]
	v_mov_b64_e32 v[76:77], v[12:13]
	v_mov_b64_e32 v[74:75], v[10:11]
	v_mov_b64_e32 v[72:73], v[8:9]
	v_mov_b64_e32 v[70:71], v[6:7]
	v_mov_b64_e32 v[68:69], v[4:5]
	v_mov_b64_e32 v[66:67], v[2:3]
	v_mov_b64_e32 v[64:65], v[0:1]
	s_waitcnt vmcnt(0)
	v_mfma_f32_32x32x16_bf16 v[80:95], v[124:127], v[108:111], 0
	v_mfma_f32_32x32x16_bf16 v[80:95], v[120:123], v[104:107], v[80:95]
	v_mfma_f32_32x32x16_bf16 v[80:95], v[116:119], v[100:103], v[80:95]
	v_mfma_f32_32x32x16_bf16 v[80:95], v[112:115], v[96:99], v[80:95]
	v_lshl_add_u64 v[14:15], v[152:153], 0, s[24:25]
	v_lshl_add_u64 v[250:251], v[154:155], 0, s[24:25]
	s_mov_b64 s[28:29], 0x10000
	s_lshr_b32 s25, s52, 6
	s_and_b32 s24, s25, 3
	s_lshl_b32 s24, s24, 11
	v_lshl_add_u64 v[14:15], s[28:29], 0, v[14:15]
	global_load_dwordx4 v[112:115], v[14:15], off
	global_load_dwordx4 v[10:13], v[14:15], off offset:1024
	global_load_dwordx4 v[6:9], v[14:15], off offset:2048
	global_load_dwordx4 v[2:5], v[14:15], off offset:3072
	s_cmp_lt_u32 s25, 4
	s_cbranch_scc0 .Lmy_pp_vsrc
	s_add_u32 s28, s24, 0x10000
	s_mov_b32 s29, 0
	v_lshl_add_u64 v[242:243], s[28:29], 0, v[14:15]
	s_mov_b32 s28, s24
	v_mov_b32_e32 v244, 0x10000
	s_nop 0
	v_lshl_add_u64 v[250:251], s[28:29], 0, v[250:251]
	s_branch .Lmy_pp_srcdone

.LBB0_728:
	s_mov_b64 s[6:7], 0
	s_cbranch_execz .LBB0_730
	v_mul_f32_e32 v0, v81, v81
	v_fmac_f32_e32 v0, v80, v80
	v_fmac_f32_e32 v0, v82, v82
	v_fmac_f32_e32 v0, v83, v83
	v_fmac_f32_e32 v0, v84, v84
	v_fmac_f32_e32 v0, v85, v85
	v_fmac_f32_e32 v0, v86, v86
	v_fmac_f32_e32 v0, v87, v87
	v_fmac_f32_e32 v0, v88, v88
	v_fmac_f32_e32 v0, v89, v89
	v_fmac_f32_e32 v0, v90, v90
	v_fmac_f32_e32 v0, v91, v91
	v_fmac_f32_e32 v0, v92, v92
	v_fmac_f32_e32 v0, v93, v93
	v_fmac_f32_e32 v0, v94, v94
	v_fmac_f32_e32 v0, v95, v95
	v_fmac_f32_e32 v0, v96, v96
	v_fmac_f32_e32 v0, v97, v97
	v_fmac_f32_e32 v0, v98, v98
	v_fmac_f32_e32 v0, v99, v99
	v_fmac_f32_e32 v0, v100, v100
	v_fmac_f32_e32 v0, v101, v101
	v_fmac_f32_e32 v0, v102, v102
	v_fmac_f32_e32 v0, v103, v103
	v_fmac_f32_e32 v0, v104, v104
	v_fmac_f32_e32 v0, v105, v105
	v_fmac_f32_e32 v0, v106, v106
	v_fmac_f32_e32 v0, v107, v107
	v_fmac_f32_e32 v0, v108, v108
	v_fmac_f32_e32 v0, v109, v109
	v_fmac_f32_e32 v0, v110, v110
	v_fmac_f32_e32 v0, v111, v111
	v_fmac_f32_e32 v0, v112, v112
	v_fmac_f32_e32 v0, v113, v113
	v_fmac_f32_e32 v0, v114, v114
	v_fmac_f32_e32 v0, v115, v115
	v_fmac_f32_e32 v0, v116, v116
	v_fmac_f32_e32 v0, v117, v117
	v_fmac_f32_e32 v0, v118, v118
	v_fmac_f32_e32 v0, v119, v119
	v_fmac_f32_e32 v0, v120, v120
	v_fmac_f32_e32 v0, v121, v121
	v_fmac_f32_e32 v0, v122, v122
	v_fmac_f32_e32 v0, v123, v123
	v_fmac_f32_e32 v0, v124, v124
	v_fmac_f32_e32 v0, v125, v125
	v_fmac_f32_e32 v0, v126, v126
	v_fmac_f32_e32 v0, v127, v127
	v_fmac_f32_e32 v0, v128, v128
	v_fmac_f32_e32 v0, v129, v129
	v_fmac_f32_e32 v0, v130, v130
	v_fmac_f32_e32 v0, v131, v131
	v_fmac_f32_e32 v0, v132, v132
	v_fmac_f32_e32 v0, v133, v133
	v_pk_mul_f32 v[10:11], v[134:135], v[134:135]
	v_pk_mul_f32 v[8:9], v[136:137], v[136:137]
	v_add_f32_e32 v0, v10, v0
	v_add_f32_e32 v0, v11, v0
	v_add_f32_e32 v0, v8, v0
	v_pk_mul_f32 v[6:7], v[138:139], v[138:139]
	v_add_f32_e32 v0, v9, v0
	v_add_f32_e32 v0, v6, v0
	v_pk_mul_f32 v[4:5], v[140:141], v[140:141]
	v_add_f32_e32 v0, v7, v0
	v_add_f32_e32 v0, v4, v0
	v_pk_mul_f32 v[2:3], v[142:143], v[142:143]
	v_add_f32_e32 v0, v5, v0
	v_add_f32_e32 v0, v2, v0
	v_add_f32_e32 v0, v3, v0
	ds_bpermute_b32 v2, v210, v0
	v_and_b32_e32 v185, 31, v240
	v_lshrrev_b32_e32 v184, 5, v194
	v_mov_b32_e32 v12, v184
	v_mov_b32_e32 v13, v185
	s_waitcnt lgkmcnt(0)
	v_add_f32_e32 v0, v0, v2
	v_fmamk_f32 v0, v0, 0x3c000000, v213
	v_cmp_gt_f32_e32 vcc, s79, v0
	v_mul_f32_e32 v2, 0x4b800000, v0
	s_load_dwordx2 s[8:9], s[48:49], 0x88
	v_cndmask_b32_e32 v0, v0, v2, vcc
	v_rsq_f32_e32 v0, v0
	v_readlane_b32 s5, v255, 1
	s_lshl_b32 s5, s5, 2
	s_waitcnt lgkmcnt(0)
	s_add_u32 s8, s8, s5
	v_mul_f32_e32 v2, 0x45800000, v0
	v_cndmask_b32_e32 v0, v0, v2, vcc
	v_add_u32_e32 v2, s4, v13
	v_ashrrev_i32_e32 v3, 31, v2
	v_lshlrev_b32_e32 v10, 2, v12
	s_addc_u32 s9, s9, 0
	v_lshlrev_b64 v[2:3], 11, v[2:3]
	v_readlane_b32 s4, v252, 26
	v_ashrrev_i32_e32 v11, 31, v10
	v_lshl_add_u64 v[2:3], s[0:1], 0, v[2:3]
	s_lshl_b32 s4, s4, 1
	s_mov_b32 s5, s56
	v_lshl_add_u64 v[6:7], v[10:11], 2, s[8:9]
	v_lshl_add_u64 v[8:9], v[2:3], 0, s[4:5]
	global_load_dwordx4 v[16:19], v[6:7], off nt
	global_load_dwordx4 v[20:23], v[6:7], off offset:32 nt
	global_load_dwordx4 v[24:27], v[6:7], off offset:64 nt
	global_load_dwordx4 v[28:31], v[6:7], off offset:96 nt
	global_load_dwordx4 v[32:35], v[6:7], off offset:128
	global_load_dwordx4 v[36:39], v[6:7], off offset:160
	global_load_dwordx4 v[40:43], v[6:7], off offset:192
	global_load_dwordx4 v[44:47], v[6:7], off offset:224
	global_load_dwordx4 v[48:51], v[6:7], off offset:256
	global_load_dwordx4 v[52:55], v[6:7], off offset:288
	global_load_dwordx4 v[56:59], v[6:7], off offset:320
	global_load_dwordx4 v[60:63], v[6:7], off offset:352
	global_load_dwordx4 v[64:67], v[6:7], off offset:384
	global_load_dwordx4 v[68:71], v[6:7], off offset:416
	global_load_dwordx4 v[72:75], v[6:7], off offset:448
	global_load_dwordx4 v[76:79], v[6:7], off offset:480
	v_mul_f32_e32 v0, v239, v0
	s_waitcnt vmcnt(0)
	v_lshl_add_u64 v[2:3], v[10:11], 2, v[8:9]
	v_pk_mul_f32 v[4:5], v[80:81], v[0:1] op_sel_hi:[1,0]
	v_pk_mul_f32 v[6:7], v[82:83], v[0:1] op_sel_hi:[1,0]
	v_pk_mul_f32 v[8:9], v[84:85], v[0:1] op_sel_hi:[1,0]
	v_pk_mul_f32 v[10:11], v[86:87], v[0:1] op_sel_hi:[1,0]
	v_pk_mul_f32 v[4:5], v[4:5], v[16:17]
	v_pk_mul_f32 v[6:7], v[6:7], v[18:19]
	v_pk_mul_f32 v[8:9], v[8:9], v[20:21]
	v_pk_mul_f32 v[10:11], v[10:11], v[22:23]
	v_cvt_pk_bf16_f32 v12, v4, v5
	v_cvt_pk_bf16_f32 v13, v6, v7
	v_cvt_pk_bf16_f32 v14, v8, v9
	v_cvt_pk_bf16_f32 v15, v10, v11
	s_nop 1
	v_permlane32_swap_b32_e32 v12, v14
	v_permlane32_swap_b32_e32 v13, v15
	global_store_dwordx4 v[2:3], v[12:15], off
	v_pk_mul_f32 v[4:5], v[88:89], v[0:1] op_sel_hi:[1,0]
	v_pk_mul_f32 v[6:7], v[90:91], v[0:1] op_sel_hi:[1,0]
	v_pk_mul_f32 v[8:9], v[92:93], v[0:1] op_sel_hi:[1,0]
	v_pk_mul_f32 v[10:11], v[94:95], v[0:1] op_sel_hi:[1,0]
	v_pk_mul_f32 v[4:5], v[4:5], v[24:25]
	v_pk_mul_f32 v[6:7], v[6:7], v[26:27]
	v_pk_mul_f32 v[8:9], v[8:9], v[28:29]
	v_pk_mul_f32 v[10:11], v[10:11], v[30:31]
	v_cvt_pk_bf16_f32 v12, v4, v5
	v_cvt_pk_bf16_f32 v13, v6, v7
	v_cvt_pk_bf16_f32 v14, v8, v9
	v_cvt_pk_bf16_f32 v15, v10, v11
	s_nop 1
	v_permlane32_swap_b32_e32 v12, v14
	v_permlane32_swap_b32_e32 v13, v15
	global_store_dwordx4 v[2:3], v[12:15], off offset:32
	v_pk_mul_f32 v[4:5], v[96:97], v[0:1] op_sel_hi:[1,0]
	v_pk_mul_f32 v[6:7], v[98:99], v[0:1] op_sel_hi:[1,0]
	v_pk_mul_f32 v[8:9], v[100:101], v[0:1] op_sel_hi:[1,0]
	v_pk_mul_f32 v[10:11], v[102:103], v[0:1] op_sel_hi:[1,0]
	v_pk_mul_f32 v[4:5], v[4:5], v[32:33]
	v_pk_mul_f32 v[6:7], v[6:7], v[34:35]
	v_pk_mul_f32 v[8:9], v[8:9], v[36:37]
	v_pk_mul_f32 v[10:11], v[10:11], v[38:39]
	v_cvt_pk_bf16_f32 v12, v4, v5
	v_cvt_pk_bf16_f32 v13, v6, v7
	v_cvt_pk_bf16_f32 v14, v8, v9
	v_cvt_pk_bf16_f32 v15, v10, v11
	s_nop 1
	v_permlane32_swap_b32_e32 v12, v14
	v_permlane32_swap_b32_e32 v13, v15
	global_store_dwordx4 v[2:3], v[12:15], off offset:64
	v_pk_mul_f32 v[4:5], v[104:105], v[0:1] op_sel_hi:[1,0]
	v_pk_mul_f32 v[6:7], v[106:107], v[0:1] op_sel_hi:[1,0]
	v_pk_mul_f32 v[8:9], v[108:109], v[0:1] op_sel_hi:[1,0]
	v_pk_mul_f32 v[10:11], v[110:111], v[0:1] op_sel_hi:[1,0]
	v_pk_mul_f32 v[4:5], v[4:5], v[40:41]
	v_pk_mul_f32 v[6:7], v[6:7], v[42:43]
	v_pk_mul_f32 v[8:9], v[8:9], v[44:45]
	v_pk_mul_f32 v[10:11], v[10:11], v[46:47]
	v_cvt_pk_bf16_f32 v12, v4, v5
	v_cvt_pk_bf16_f32 v13, v6, v7
	v_cvt_pk_bf16_f32 v14, v8, v9
	v_cvt_pk_bf16_f32 v15, v10, v11
	s_nop 1
	v_permlane32_swap_b32_e32 v12, v14
	v_permlane32_swap_b32_e32 v13, v15
	global_store_dwordx4 v[2:3], v[12:15], off offset:96
	v_pk_mul_f32 v[4:5], v[112:113], v[0:1] op_sel_hi:[1,0]
	v_pk_mul_f32 v[6:7], v[114:115], v[0:1] op_sel_hi:[1,0]
	v_pk_mul_f32 v[8:9], v[116:117], v[0:1] op_sel_hi:[1,0]
	v_pk_mul_f32 v[10:11], v[118:119], v[0:1] op_sel_hi:[1,0]
	v_pk_mul_f32 v[4:5], v[4:5], v[48:49]
	v_pk_mul_f32 v[6:7], v[6:7], v[50:51]
	v_pk_mul_f32 v[8:9], v[8:9], v[52:53]
	v_pk_mul_f32 v[10:11], v[10:11], v[54:55]
	v_cvt_pk_bf16_f32 v12, v4, v5
	v_cvt_pk_bf16_f32 v13, v6, v7
	v_cvt_pk_bf16_f32 v14, v8, v9
	v_cvt_pk_bf16_f32 v15, v10, v11
	s_nop 1
	v_permlane32_swap_b32_e32 v12, v14
	v_permlane32_swap_b32_e32 v13, v15
	global_store_dwordx4 v[2:3], v[12:15], off offset:128
	v_pk_mul_f32 v[4:5], v[120:121], v[0:1] op_sel_hi:[1,0]
	v_pk_mul_f32 v[6:7], v[122:123], v[0:1] op_sel_hi:[1,0]
	v_pk_mul_f32 v[8:9], v[124:125], v[0:1] op_sel_hi:[1,0]
	v_pk_mul_f32 v[10:11], v[126:127], v[0:1] op_sel_hi:[1,0]
	v_pk_mul_f32 v[4:5], v[4:5], v[56:57]
	v_pk_mul_f32 v[6:7], v[6:7], v[58:59]
	v_pk_mul_f32 v[8:9], v[8:9], v[60:61]
	v_pk_mul_f32 v[10:11], v[10:11], v[62:63]
	v_cvt_pk_bf16_f32 v12, v4, v5
	v_cvt_pk_bf16_f32 v13, v6, v7
	v_cvt_pk_bf16_f32 v14, v8, v9
	v_cvt_pk_bf16_f32 v15, v10, v11
	s_nop 1
	v_permlane32_swap_b32_e32 v12, v14
	v_permlane32_swap_b32_e32 v13, v15
	global_store_dwordx4 v[2:3], v[12:15], off offset:160
	v_pk_mul_f32 v[4:5], v[128:129], v[0:1] op_sel_hi:[1,0]
	v_pk_mul_f32 v[6:7], v[130:131], v[0:1] op_sel_hi:[1,0]
	v_pk_mul_f32 v[8:9], v[132:133], v[0:1] op_sel_hi:[1,0]
	v_pk_mul_f32 v[10:11], v[134:135], v[0:1] op_sel_hi:[1,0]
	v_pk_mul_f32 v[4:5], v[4:5], v[64:65]
	v_pk_mul_f32 v[6:7], v[6:7], v[66:67]
	v_pk_mul_f32 v[8:9], v[8:9], v[68:69]
	v_pk_mul_f32 v[10:11], v[10:11], v[70:71]
	v_cvt_pk_bf16_f32 v12, v4, v5
	v_cvt_pk_bf16_f32 v13, v6, v7
	v_cvt_pk_bf16_f32 v14, v8, v9
	v_cvt_pk_bf16_f32 v15, v10, v11
	s_nop 1
	v_permlane32_swap_b32_e32 v12, v14
	v_permlane32_swap_b32_e32 v13, v15
	global_store_dwordx4 v[2:3], v[12:15], off offset:192
	v_pk_mul_f32 v[4:5], v[136:137], v[0:1] op_sel_hi:[1,0]
	v_pk_mul_f32 v[6:7], v[138:139], v[0:1] op_sel_hi:[1,0]
	v_pk_mul_f32 v[8:9], v[140:141], v[0:1] op_sel_hi:[1,0]
	v_pk_mul_f32 v[10:11], v[142:143], v[0:1] op_sel_hi:[1,0]
	v_pk_mul_f32 v[4:5], v[4:5], v[72:73]
	v_pk_mul_f32 v[6:7], v[6:7], v[74:75]
	v_pk_mul_f32 v[8:9], v[8:9], v[76:77]
	v_pk_mul_f32 v[10:11], v[10:11], v[78:79]
	v_cvt_pk_bf16_f32 v12, v4, v5
	v_cvt_pk_bf16_f32 v13, v6, v7
	v_cvt_pk_bf16_f32 v14, v8, v9
	v_cvt_pk_bf16_f32 v15, v10, v11
	s_nop 1
	v_permlane32_swap_b32_e32 v12, v14
	v_permlane32_swap_b32_e32 v13, v15
	global_store_dwordx4 v[2:3], v[12:15], off offset:224

.LBB0_734:
	s_xor_b64 s[18:19], s[16:17], -1
	s_lshl_b32 s11, s10, 7
	v_mov_b32_e32 v0, v185
	v_mov_b32_e32 v4, v184
	s_add_u32 s12, s5, s11
	s_addc_u32 s13, s7, 0
	v_mov_b64_e32 v[2:3], s[12:13]
	v_lshlrev_b32_e32 v4, 3, v4
	v_mad_i64_i32 v[2:3], s[12:13], v0, s76, v[2:3]
	v_ashrrev_i32_e32 v5, 31, v4
	s_lshl_b32 s10, s10, 12
	v_readlane_b32 s11, v252, 35
	v_lshl_add_u64 v[2:3], v[4:5], 1, v[2:3]
	s_or_b32 s12, s10, s11
	s_mov_b32 s13, s56
	global_load_dwordx4 v[108:111], v[2:3], off nt
	global_load_dwordx4 v[104:107], v[2:3], off offset:32 nt
	global_load_dwordx4 v[100:103], v[2:3], off offset:64 nt
	global_load_dwordx4 v[96:99], v[2:3], off offset:96 nt
	v_lshl_add_u64 v[2:3], v[152:153], 0, s[12:13]
	global_load_dwordx4 v[124:127], v[2:3], off
	global_load_dwordx4 v[120:123], v[2:3], off offset:1024
	global_load_dwordx4 v[116:119], v[2:3], off offset:2048
	global_load_dwordx4 v[112:115], v[2:3], off offset:3072
	v_mov_b32_e32 v14, v1
	v_mov_b32_e32 v15, v1
	s_add_u32 s24, s8, s12
	v_mov_b32_e32 v0, v1
	v_mov_b32_e32 v2, v1
	v_mov_b32_e32 v3, v1
	v_mov_b32_e32 v4, v1
	v_mov_b32_e32 v5, v1
	v_mov_b32_e32 v6, v1
	v_mov_b32_e32 v7, v1
	v_mov_b32_e32 v8, v1
	v_mov_b32_e32 v9, v1
	v_mov_b32_e32 v10, v1
	v_mov_b32_e32 v11, v1
	v_mov_b32_e32 v12, v1
	v_mov_b32_e32 v13, v1
	v_mov_b64_e32 v[30:31], v[14:15]
	v_mov_b64_e32 v[46:47], v[14:15]
	v_mov_b64_e32 v[62:63], v[14:15]
	v_mov_b64_e32 v[78:79], v[14:15]
	s_mov_b32 s10, 7
	s_addc_u32 s25, s9, 0
	v_mov_b32_e32 v187, 0
	v_mov_b32_e32 v188, 0xf149f2ca
	s_mov_b64 s[26:27], s[14:15]
	v_mov_b64_e32 v[28:29], v[12:13]
	v_mov_b64_e32 v[26:27], v[10:11]
	v_mov_b64_e32 v[24:25], v[8:9]
	v_mov_b64_e32 v[22:23], v[6:7]
	v_mov_b64_e32 v[20:21], v[4:5]
	v_mov_b64_e32 v[18:19], v[2:3]
	v_mov_b64_e32 v[16:17], v[0:1]
	v_mov_b64_e32 v[44:45], v[12:13]
	v_mov_b64_e32 v[42:43], v[10:11]
	v_mov_b64_e32 v[40:41], v[8:9]
	v_mov_b64_e32 v[38:39], v[6:7]
	v_mov_b64_e32 v[36:37], v[4:5]
	v_mov_b64_e32 v[34:35], v[2:3]
	v_mov_b64_e32 v[32:33], v[0:1]
	v_mov_b64_e32 v[60:61], v[12:13]
	v_mov_b64_e32 v[58:59], v[10:11]
	v_mov_b64_e32 v[56:57], v[8:9]
	v_mov_b64_e32 v[54:55], v[6:7]
	v_mov_b64_e32 v[52:53], v[4:5]
	v_mov_b64_e32 v[50:51], v[2:3]
	v_mov_b64_e32 v[48:49], v[0:1]
	v_mov_b64_e32 v[76:77], v[12:13]
	v_mov_b64_e32 v[74:75], v[10:11]
	v_mov_b64_e32 v[72:73], v[8:9]
	v_mov_b64_e32 v[70:71], v[6:7]
	v_mov_b64_e32 v[68:69], v[4:5]
	v_mov_b64_e32 v[66:67], v[2:3]
	v_mov_b64_e32 v[64:65], v[0:1]
	s_branch .LBB0_736

.LBB0_744:
	v_mul_f32_e32 v0, v129, v129
	v_fmac_f32_e32 v0, v128, v128
	v_fmac_f32_e32 v0, v130, v130
	v_fmac_f32_e32 v0, v131, v131
	v_fmac_f32_e32 v0, v132, v132
	v_fmac_f32_e32 v0, v133, v133
	v_fmac_f32_e32 v0, v134, v134
	v_fmac_f32_e32 v0, v135, v135
	v_fmac_f32_e32 v0, v136, v136
	v_fmac_f32_e32 v0, v137, v137
	v_fmac_f32_e32 v0, v138, v138
	v_fmac_f32_e32 v0, v139, v139
	v_fmac_f32_e32 v0, v140, v140
	v_fmac_f32_e32 v0, v141, v141
	v_fmac_f32_e32 v0, v142, v142
	v_fmac_f32_e32 v0, v143, v143
	v_fmac_f32_e32 v0, v112, v112
	v_fmac_f32_e32 v0, v113, v113
	v_fmac_f32_e32 v0, v114, v114
	v_fmac_f32_e32 v0, v115, v115
	v_fmac_f32_e32 v0, v116, v116
	v_fmac_f32_e32 v0, v117, v117
	v_fmac_f32_e32 v0, v118, v118
	v_fmac_f32_e32 v0, v119, v119
	v_fmac_f32_e32 v0, v120, v120
	v_fmac_f32_e32 v0, v121, v121
	v_fmac_f32_e32 v0, v122, v122
	v_fmac_f32_e32 v0, v123, v123
	v_fmac_f32_e32 v0, v124, v124
	v_fmac_f32_e32 v0, v125, v125
	v_fmac_f32_e32 v0, v126, v126
	v_fmac_f32_e32 v0, v127, v127
	v_fmac_f32_e32 v0, v96, v96
	v_fmac_f32_e32 v0, v97, v97
	v_fmac_f32_e32 v0, v98, v98
	v_fmac_f32_e32 v0, v99, v99
	v_fmac_f32_e32 v0, v100, v100
	v_fmac_f32_e32 v0, v101, v101
	v_fmac_f32_e32 v0, v102, v102
	v_fmac_f32_e32 v0, v103, v103
	v_fmac_f32_e32 v0, v104, v104
	v_fmac_f32_e32 v0, v105, v105
	v_fmac_f32_e32 v0, v106, v106
	v_fmac_f32_e32 v0, v107, v107
	v_fmac_f32_e32 v0, v108, v108
	v_fmac_f32_e32 v0, v109, v109
	v_fmac_f32_e32 v0, v110, v110
	v_fmac_f32_e32 v0, v111, v111
	v_fmac_f32_e32 v0, v80, v80
	v_fmac_f32_e32 v0, v81, v81
	v_fmac_f32_e32 v0, v82, v82
	v_fmac_f32_e32 v0, v83, v83
	v_fmac_f32_e32 v0, v84, v84
	v_fmac_f32_e32 v0, v85, v85
	v_pk_mul_f32 v[10:11], v[86:87], v[86:87]
	v_pk_mul_f32 v[8:9], v[88:89], v[88:89]
	v_add_f32_e32 v0, v10, v0
	v_add_f32_e32 v0, v11, v0
	v_add_f32_e32 v0, v8, v0
	v_pk_mul_f32 v[6:7], v[90:91], v[90:91]
	v_add_f32_e32 v0, v9, v0
	v_add_f32_e32 v0, v6, v0
	v_pk_mul_f32 v[4:5], v[92:93], v[92:93]
	v_add_f32_e32 v0, v7, v0
	v_add_f32_e32 v0, v4, v0
	v_pk_mul_f32 v[2:3], v[94:95], v[94:95]
	v_add_f32_e32 v0, v5, v0
	v_add_f32_e32 v0, v2, v0
	v_add_f32_e32 v0, v3, v0
	ds_bpermute_b32 v2, v210, v0
	s_load_dwordx2 s[8:9], s[48:49], 0x88
	v_readlane_b32 s5, v255, 1
	s_lshl_b32 s5, s5, 2
	s_waitcnt lgkmcnt(0)
	v_add_f32_e32 v0, v0, v2
	v_fmamk_f32 v0, v0, 0x3c000000, v213
	v_cmp_gt_f32_e32 vcc, s79, v0
	v_mul_f32_e32 v2, 0x4b800000, v0
	s_add_u32 s8, s8, s5
	v_cndmask_b32_e32 v0, v0, v2, vcc
	v_rsq_f32_e32 v0, v0
	v_lshlrev_b32_e32 v10, 2, v184
	s_addc_u32 s9, s9, 0
	v_ashrrev_i32_e32 v11, 31, v10
	v_mul_f32_e32 v2, 0x45800000, v0
	v_cndmask_b32_e32 v0, v0, v2, vcc
	v_add_u32_e32 v2, s4, v185
	v_ashrrev_i32_e32 v3, 31, v2
	v_lshlrev_b64 v[2:3], 11, v[2:3]
	v_lshl_add_u64 v[2:3], s[0:1], 0, v[2:3]
	s_mov_b32 s7, s56
	v_lshl_add_u64 v[6:7], v[10:11], 2, s[8:9]
	v_lshl_add_u64 v[8:9], v[2:3], 0, s[6:7]
	global_load_dwordx4 v[16:19], v[6:7], off nt
	global_load_dwordx4 v[20:23], v[6:7], off offset:32 nt
	global_load_dwordx4 v[24:27], v[6:7], off offset:64 nt
	global_load_dwordx4 v[28:31], v[6:7], off offset:96 nt
	global_load_dwordx4 v[32:35], v[6:7], off offset:128
	global_load_dwordx4 v[36:39], v[6:7], off offset:160
	global_load_dwordx4 v[40:43], v[6:7], off offset:192
	global_load_dwordx4 v[44:47], v[6:7], off offset:224
	global_load_dwordx4 v[48:51], v[6:7], off offset:256
	global_load_dwordx4 v[52:55], v[6:7], off offset:288
	global_load_dwordx4 v[56:59], v[6:7], off offset:320
	global_load_dwordx4 v[60:63], v[6:7], off offset:352
	global_load_dwordx4 v[64:67], v[6:7], off offset:384
	global_load_dwordx4 v[68:71], v[6:7], off offset:416
	global_load_dwordx4 v[72:75], v[6:7], off offset:448
	global_load_dwordx4 v[76:79], v[6:7], off offset:480
	v_mul_f32_e32 v0, v239, v0
	s_waitcnt vmcnt(0)
	v_lshl_add_u64 v[2:3], v[10:11], 2, v[8:9]
	v_pk_mul_f32 v[4:5], v[128:129], v[0:1] op_sel_hi:[1,0]
	v_pk_mul_f32 v[6:7], v[130:131], v[0:1] op_sel_hi:[1,0]
	v_pk_mul_f32 v[8:9], v[132:133], v[0:1] op_sel_hi:[1,0]
	v_pk_mul_f32 v[10:11], v[134:135], v[0:1] op_sel_hi:[1,0]
	v_pk_mul_f32 v[4:5], v[4:5], v[16:17]
	v_pk_mul_f32 v[6:7], v[6:7], v[18:19]
	v_pk_mul_f32 v[8:9], v[8:9], v[20:21]
	v_pk_mul_f32 v[10:11], v[10:11], v[22:23]
	v_cvt_pk_bf16_f32 v12, v4, v5
	v_cvt_pk_bf16_f32 v13, v6, v7
	v_cvt_pk_bf16_f32 v14, v8, v9
	v_cvt_pk_bf16_f32 v15, v10, v11
	s_nop 1
	v_permlane32_swap_b32_e32 v12, v14
	v_permlane32_swap_b32_e32 v13, v15
	global_store_dwordx4 v[2:3], v[12:15], off
	v_pk_mul_f32 v[4:5], v[136:137], v[0:1] op_sel_hi:[1,0]
	v_pk_mul_f32 v[6:7], v[138:139], v[0:1] op_sel_hi:[1,0]
	v_pk_mul_f32 v[8:9], v[140:141], v[0:1] op_sel_hi:[1,0]
	v_pk_mul_f32 v[10:11], v[142:143], v[0:1] op_sel_hi:[1,0]
	v_pk_mul_f32 v[4:5], v[4:5], v[24:25]
	v_pk_mul_f32 v[6:7], v[6:7], v[26:27]
	v_pk_mul_f32 v[8:9], v[8:9], v[28:29]
	v_pk_mul_f32 v[10:11], v[10:11], v[30:31]
	v_cvt_pk_bf16_f32 v12, v4, v5
	v_cvt_pk_bf16_f32 v13, v6, v7
	v_cvt_pk_bf16_f32 v14, v8, v9
	v_cvt_pk_bf16_f32 v15, v10, v11
	s_nop 1
	v_permlane32_swap_b32_e32 v12, v14
	v_permlane32_swap_b32_e32 v13, v15
	global_store_dwordx4 v[2:3], v[12:15], off offset:32
	v_pk_mul_f32 v[4:5], v[112:113], v[0:1] op_sel_hi:[1,0]
	v_pk_mul_f32 v[6:7], v[114:115], v[0:1] op_sel_hi:[1,0]
	v_pk_mul_f32 v[8:9], v[116:117], v[0:1] op_sel_hi:[1,0]
	v_pk_mul_f32 v[10:11], v[118:119], v[0:1] op_sel_hi:[1,0]
	v_pk_mul_f32 v[4:5], v[4:5], v[32:33]
	v_pk_mul_f32 v[6:7], v[6:7], v[34:35]
	v_pk_mul_f32 v[8:9], v[8:9], v[36:37]
	v_pk_mul_f32 v[10:11], v[10:11], v[38:39]
	v_cvt_pk_bf16_f32 v12, v4, v5
	v_cvt_pk_bf16_f32 v13, v6, v7
	v_cvt_pk_bf16_f32 v14, v8, v9
	v_cvt_pk_bf16_f32 v15, v10, v11
	s_nop 1
	v_permlane32_swap_b32_e32 v12, v14
	v_permlane32_swap_b32_e32 v13, v15
	global_store_dwordx4 v[2:3], v[12:15], off offset:64
	v_pk_mul_f32 v[4:5], v[120:121], v[0:1] op_sel_hi:[1,0]
	v_pk_mul_f32 v[6:7], v[122:123], v[0:1] op_sel_hi:[1,0]
	v_pk_mul_f32 v[8:9], v[124:125], v[0:1] op_sel_hi:[1,0]
	v_pk_mul_f32 v[10:11], v[126:127], v[0:1] op_sel_hi:[1,0]
	v_pk_mul_f32 v[4:5], v[4:5], v[40:41]
	v_pk_mul_f32 v[6:7], v[6:7], v[42:43]
	v_pk_mul_f32 v[8:9], v[8:9], v[44:45]
	v_pk_mul_f32 v[10:11], v[10:11], v[46:47]
	v_cvt_pk_bf16_f32 v12, v4, v5
	v_cvt_pk_bf16_f32 v13, v6, v7
	v_cvt_pk_bf16_f32 v14, v8, v9
	v_cvt_pk_bf16_f32 v15, v10, v11
	s_nop 1
	v_permlane32_swap_b32_e32 v12, v14
	v_permlane32_swap_b32_e32 v13, v15
	global_store_dwordx4 v[2:3], v[12:15], off offset:96
	v_pk_mul_f32 v[4:5], v[96:97], v[0:1] op_sel_hi:[1,0]
	v_pk_mul_f32 v[6:7], v[98:99], v[0:1] op_sel_hi:[1,0]
	v_pk_mul_f32 v[8:9], v[100:101], v[0:1] op_sel_hi:[1,0]
	v_pk_mul_f32 v[10:11], v[102:103], v[0:1] op_sel_hi:[1,0]
	v_pk_mul_f32 v[4:5], v[4:5], v[48:49]
	v_pk_mul_f32 v[6:7], v[6:7], v[50:51]
	v_pk_mul_f32 v[8:9], v[8:9], v[52:53]
	v_pk_mul_f32 v[10:11], v[10:11], v[54:55]
	v_cvt_pk_bf16_f32 v12, v4, v5
	v_cvt_pk_bf16_f32 v13, v6, v7
	v_cvt_pk_bf16_f32 v14, v8, v9
	v_cvt_pk_bf16_f32 v15, v10, v11
	s_nop 1
	v_permlane32_swap_b32_e32 v12, v14
	v_permlane32_swap_b32_e32 v13, v15
	global_store_dwordx4 v[2:3], v[12:15], off offset:128
	v_pk_mul_f32 v[4:5], v[104:105], v[0:1] op_sel_hi:[1,0]
	v_pk_mul_f32 v[6:7], v[106:107], v[0:1] op_sel_hi:[1,0]
	v_pk_mul_f32 v[8:9], v[108:109], v[0:1] op_sel_hi:[1,0]
	v_pk_mul_f32 v[10:11], v[110:111], v[0:1] op_sel_hi:[1,0]
	v_pk_mul_f32 v[4:5], v[4:5], v[56:57]
	v_pk_mul_f32 v[6:7], v[6:7], v[58:59]
	v_pk_mul_f32 v[8:9], v[8:9], v[60:61]
	v_pk_mul_f32 v[10:11], v[10:11], v[62:63]
	v_cvt_pk_bf16_f32 v12, v4, v5
	v_cvt_pk_bf16_f32 v13, v6, v7
	v_cvt_pk_bf16_f32 v14, v8, v9
	v_cvt_pk_bf16_f32 v15, v10, v11
	s_nop 1
	v_permlane32_swap_b32_e32 v12, v14
	v_permlane32_swap_b32_e32 v13, v15
	global_store_dwordx4 v[2:3], v[12:15], off offset:160
	v_pk_mul_f32 v[4:5], v[80:81], v[0:1] op_sel_hi:[1,0]
	v_pk_mul_f32 v[6:7], v[82:83], v[0:1] op_sel_hi:[1,0]
	v_pk_mul_f32 v[8:9], v[84:85], v[0:1] op_sel_hi:[1,0]
	v_pk_mul_f32 v[10:11], v[86:87], v[0:1] op_sel_hi:[1,0]
	v_pk_mul_f32 v[4:5], v[4:5], v[64:65]
	v_pk_mul_f32 v[6:7], v[6:7], v[66:67]
	v_pk_mul_f32 v[8:9], v[8:9], v[68:69]
	v_pk_mul_f32 v[10:11], v[10:11], v[70:71]
	v_cvt_pk_bf16_f32 v12, v4, v5
	v_cvt_pk_bf16_f32 v13, v6, v7
	v_cvt_pk_bf16_f32 v14, v8, v9
	v_cvt_pk_bf16_f32 v15, v10, v11
	s_nop 1
	v_permlane32_swap_b32_e32 v12, v14
	v_permlane32_swap_b32_e32 v13, v15
	global_store_dwordx4 v[2:3], v[12:15], off offset:192
	v_pk_mul_f32 v[4:5], v[88:89], v[0:1] op_sel_hi:[1,0]
	v_pk_mul_f32 v[6:7], v[90:91], v[0:1] op_sel_hi:[1,0]
	v_pk_mul_f32 v[8:9], v[92:93], v[0:1] op_sel_hi:[1,0]
	v_pk_mul_f32 v[10:11], v[94:95], v[0:1] op_sel_hi:[1,0]
	v_pk_mul_f32 v[4:5], v[4:5], v[72:73]
	v_pk_mul_f32 v[6:7], v[6:7], v[74:75]
	v_pk_mul_f32 v[8:9], v[8:9], v[76:77]
	v_pk_mul_f32 v[10:11], v[10:11], v[78:79]
	v_cvt_pk_bf16_f32 v12, v4, v5
	v_cvt_pk_bf16_f32 v13, v6, v7
	v_cvt_pk_bf16_f32 v14, v8, v9
	v_cvt_pk_bf16_f32 v15, v10, v11
	s_nop 1
	v_permlane32_swap_b32_e32 v12, v14
	v_permlane32_swap_b32_e32 v13, v15
	global_store_dwordx4 v[2:3], v[12:15], off offset:224
